# attention tile loop edge rotation: head skip test and exit test evaluated before the back-edge barrier, loop head moved out of line
# baseline (speedup 1.0000x reference)
; __device__ __forceinline__ void unit(const Ctx& C, int xq, int idx, LAS unsigned char* lds) {
;     ...
;     for (int j = 0; j < nt; j += 2) {
;         if (valid && j <= cw) tile(lds, j);
.LBB0_515:
	s_add_i32 s93, s92, -4
	s_cmp_le_u32 s93, s86
	s_cselect_b64 s[34:35], -1, 0
	s_and_b64 s[34:35], s[42:43], s[34:35]
	s_andn2_b64 vcc, exec, s[34:35]
	s_cbranch_vccnz .LBB0_523
	s_branch .Lmy_att516

; #define LAS __attribute__((address_space(3)))
; #define ATT_STORE(buf, kr, vr) do { LAS unsigned char* sb_ = lds + (buf) * STAGE; \
;         _Pragma("unroll") for (int i_ = 0; i_ < 2; ++i_) { const int id_ = tid + 512 * i_; \
;             *(LAS u32x4*)(sb_ + ((id_ & 15) >> 3) * KSL + (id_ >> 4) * 144 + (id_ & 7) * 16) = kr[i_]; *(LAS u32x4*)(sb_ + KBUF + (id_ >> 3) * 144 + (id_ & 7) * 16) = vr[i_]; } } while (0)
; __device__ __forceinline__ void unit(const Ctx& C, int xq, int idx, LAS unsigned char* lds) {
;     ...
;         for (int d0 = 0; d0 < 4; ++d0) {
;             const bf16x8 a0 = *(const LAS bf16x8*)(sb + koff + d0 * 32), a1 = *(const LAS bf16x8*)(sb + koff + 32 * 144 + d0 * 32);
;             S0 = __builtin_amdgcn_mfma_f32_32x32x16_bf16(a0, qf[d0], S0, 0, 0, 0);
;             S1 = __builtin_amdgcn_mfma_f32_32x32x16_bf16(a1, qf[d0], S1, 0, 0, 0);
;         }
;         if (j + 3 <= cw) {
; #pragma unroll
;             for (int r = 0; r < 16; ++r) { float a_ = __builtin_fmaf(S0[r], C2, b15), b_ = __builtin_fmaf(S1[r], C2, b15); asm("" : "+v"(a_)); asm("" : "+v"(b_)); S0[r] = a_; S1[r] = b_; }
;     ...
;     for (int j = 0; j < nt; j += 2) {
;         if (valid && j <= cw) tile(lds, j);
;         if (j + 1 < nt) ATT_STORE(1, krA, vrA);
;         if (j + 3 < nt) ATT_LOAD(j + 3, krA, vrA);
;         __syncthreads();
;         if (j + 1 >= nt) break;
;         if (valid && j + 1 <= cw) tile(lds + STAGE, j + 1);
;         if (j + 2 < nt) ATT_STORE(0, krB, vrB);
;         if (j + 4 < nt) ATT_LOAD(j + 4, krB, vrB);
;         __syncthreads();
.LBB0_514:
	s_add_i32 s92, s92, 2
	s_add_u32 s52, s52, 0x100
	s_addc_u32 s53, s53, 0
	s_add_u32 s54, s54, 0x240000
	s_addc_u32 s55, s55, 0
	s_add_i32 s91, s91, 2
	s_cmp_ge_u32 s34, s37
	v_add_u32_e32 v216, 0x200, v216
	s_cselect_b64 s[56:57], -1, 0
	s_add_i32 s93, s92, -4
	s_cmp_le_u32 s93, s86
	s_cselect_b64 s[34:35], -1, 0
	s_and_b64 s[34:35], s[42:43], s[34:35]
	s_and_b64 vcc, exec, s[56:57]
	s_waitcnt lgkmcnt(0)
	s_barrier
	s_cbranch_vccnz .LBB0_550
	s_andn2_b64 vcc, exec, s[34:35]
	s_cbranch_vccnz .LBB0_523
.Lmy_att516:
	ds_read_b128 v[64:67], v193
	ds_read_b128 v[80:83], v193 offset:4608
	ds_read_b128 v[68:71], v193 offset:32
	ds_read_b128 v[72:75], v193 offset:4640
	ds_read_b128 v[84:87], v193 offset:64
	ds_read_b128 v[88:91], v193 offset:4672
	ds_read_b128 v[92:95], v193 offset:96
	ds_read_b128 v[222:225], v193 offset:4704
	s_add_i32 s4, s92, -1
	s_mov_b64 s[56:57], -1
	s_cmp_gt_u32 s4, s86
	s_waitcnt lgkmcnt(7)
	v_mfma_f32_32x32x16_bf16 v[112:127], v[64:67], v[128:131], 0
	s_waitcnt lgkmcnt(6)
	v_mfma_f32_32x32x16_bf16 v[96:111], v[80:83], v[128:131], 0
	s_waitcnt lgkmcnt(5)
	v_mfma_f32_32x32x16_bf16 v[112:127], v[68:71], v[132:135], v[112:127]
	s_waitcnt lgkmcnt(4)
	v_mfma_f32_32x32x16_bf16 v[96:111], v[72:75], v[132:135], v[96:111]
	s_waitcnt lgkmcnt(3)
	v_mfma_f32_32x32x16_bf16 v[112:127], v[84:87], v[136:139], v[112:127]
	s_waitcnt lgkmcnt(2)
	v_mfma_f32_32x32x16_bf16 v[96:111], v[88:91], v[136:139], v[96:111]
	s_waitcnt lgkmcnt(1)
	v_mfma_f32_32x32x16_bf16 v[112:127], v[92:95], v[140:143], v[112:127]
	s_waitcnt lgkmcnt(0)
	v_mfma_f32_32x32x16_bf16 v[96:111], v[222:225], v[140:143], v[96:111]
	s_cbranch_scc1 .LBB0_518
	s_nop 8
	v_fmamk_f32 v80, v112, 0x3e38aa3b, v191
	s_nop 0
	v_fmamk_f32 v64, v96, 0x3e38aa3b, v191
	v_fmamk_f32 v81, v113, 0x3e38aa3b, v191
	v_fmamk_f32 v65, v97, 0x3e38aa3b, v191
	v_fmamk_f32 v82, v114, 0x3e38aa3b, v191
	v_fmamk_f32 v66, v98, 0x3e38aa3b, v191
	v_fmamk_f32 v83, v115, 0x3e38aa3b, v191
	v_fmamk_f32 v67, v99, 0x3e38aa3b, v191
	v_fmamk_f32 v84, v116, 0x3e38aa3b, v191
	v_fmamk_f32 v68, v100, 0x3e38aa3b, v191
	v_fmamk_f32 v85, v117, 0x3e38aa3b, v191
	v_fmamk_f32 v69, v101, 0x3e38aa3b, v191
	v_fmamk_f32 v86, v118, 0x3e38aa3b, v191
	v_fmamk_f32 v70, v102, 0x3e38aa3b, v191
	v_fmamk_f32 v87, v119, 0x3e38aa3b, v191
	v_fmamk_f32 v71, v103, 0x3e38aa3b, v191
	v_fmamk_f32 v88, v120, 0x3e38aa3b, v191
	v_fmamk_f32 v72, v104, 0x3e38aa3b, v191
	v_fmamk_f32 v89, v121, 0x3e38aa3b, v191
	v_fmamk_f32 v73, v105, 0x3e38aa3b, v191
	v_fmamk_f32 v90, v122, 0x3e38aa3b, v191
	v_fmamk_f32 v74, v106, 0x3e38aa3b, v191
	v_fmamk_f32 v91, v123, 0x3e38aa3b, v191
	v_fmamk_f32 v75, v107, 0x3e38aa3b, v191
	v_fmamk_f32 v92, v124, 0x3e38aa3b, v191
	v_fmamk_f32 v76, v108, 0x3e38aa3b, v191
	v_fmamk_f32 v93, v125, 0x3e38aa3b, v191
	v_fmamk_f32 v77, v109, 0x3e38aa3b, v191
	v_fmamk_f32 v94, v126, 0x3e38aa3b, v191
	v_fmamk_f32 v78, v110, 0x3e38aa3b, v191
	v_fmamk_f32 v95, v127, 0x3e38aa3b, v191
	v_fmamk_f32 v79, v111, 0x3e38aa3b, v191
	s_mov_b64 s[56:57], 0
